# prologue modulation GEMV: non-temporal hint on the once-read f32 w_ada weight loads (on top of the nt row-pass / out-projection ring)
# speedup vs baseline: 1.0022x; 1.0022x over previous
; __device__ __forceinline__ void p0_mod_item(const Params& p, LAS unsigned char* lds, int item) {
;     ...
;     for (int u = tid; u < NBATCH * DM; u += NTHREADS) { const float v = p.c[u]; cs[u] = v / (1.0f + __expf(-v)); }
;     __syncthreads();
;     const int j0 = item * 64, l16 = tid & 15, rs = tid >> 4;
;     f32x4 acc[8];
; #pragma unroll
;     for (int b = 0; b < 8; ++b) acc[b] = (f32x4){0.f, 0.f, 0.f, 0.f};
; #pragma unroll 32
;     for (int pass = 0; pass < 32; ++pass) { const int i = pass * 32 + rs; const f32x4 w = *(const f32x4*)(p.w_ada + (size_t)i * NMOD + j0 + 4 * l16);
; #pragma unroll
;         for (int b = 0; b < 8; ++b) acc[b] += cs[b * DM + i] * w; }
.LBB0_28:
	global_load_dword v4, v[0:1], off
	v_add_u32_e32 v3, 0x200, v3
	v_cmp_lt_u32_e32 vcc, s19, v3
	s_or_b64 s[14:15], vcc, s[14:15]
	v_lshl_add_u64 v[0:1], v[0:1], 0, s[4:5]
	s_waitcnt vmcnt(0)
	v_mul_f32_e32 v5, 0xbfb8aa3b, v4
	v_exp_f32_e32 v5, v5
	s_nop 0
	v_add_f32_e32 v5, 1.0, v5
	v_div_scale_f32 v6, s[10:11], v5, v5, v4
	v_rcp_f32_e32 v7, v6
	v_div_scale_f32 v8, vcc, v4, v5, v4
	v_fma_f32 v9, -v6, v7, 1.0
	v_fmac_f32_e32 v7, v9, v7
	v_mul_f32_e32 v9, v8, v7
	v_fma_f32 v10, -v6, v9, v8
	v_fmac_f32_e32 v9, v10, v7
	v_fma_f32 v6, -v6, v9, v8
	v_div_fmas_f32 v6, v6, v7, v9
	v_div_fixup_f32 v4, v6, v5, v4
	ds_write_b32 v2, v4
	v_add_u32_e32 v2, 0x800, v2
	s_andn2_b64 exec, exec, s[14:15]
	s_cbranch_execnz .LBB0_28
	s_or_b64 exec, exec, s[14:15]
	s_lshl_b32 s14, s23, 6
	s_ashr_i32 s15, s14, 31
	v_lshl_add_u64 v[100:101], s[14:15], 2, v[30:31]
	v_lshl_add_u64 v[8:9], v[100:101], 0, v[44:45]
	v_add_co_u32_e32 v4, vcc, s20, v8
	s_waitcnt lgkmcnt(0)
	s_barrier
	global_load_dwordx4 v[0:3], v[8:9], off nt
	v_addc_co_u32_e32 v5, vcc, 0, v9, vcc
	global_load_dwordx4 v[12:15], v[4:5], off nt
	v_add_co_u32_e32 v4, vcc, s21, v8
	v_lshl_add_u64 v[16:17], v[100:101], 0, v[46:47]
	s_nop 0
	v_addc_co_u32_e32 v5, vcc, 0, v9, vcc
	v_add_co_u32_e32 v8, vcc, s22, v8
	global_load_dwordx4 v[4:7], v[4:5], off nt
	s_nop 0
	v_addc_co_u32_e32 v9, vcc, 0, v9, vcc
	global_load_dwordx4 v[8:11], v[8:9], off nt
	v_lshl_add_u64 v[18:19], v[100:101], 0, v[48:49]
	ds_read2_b32 v[104:105], v126 offset1:32
	v_add_u32_e32 v79, 0x1000, v126
	v_add_u32_e32 v77, 0x2000, v126
	v_add_u32_e32 v75, 0x3000, v126
	v_add_u32_e32 v73, 0x4000, v126
	v_add_u32_e32 v71, 0x5000, v126
	v_add_u32_e32 v69, 0x6000, v126
	v_add_u32_e32 v81, 0x7000, v126
	ds_read2_b32 v[24:25], v126 offset0:64 offset1:96
	ds_read2_b32 v[156:157], v79 offset1:32
	ds_read2_b32 v[158:159], v77 offset1:32
	ds_read2_b32 v[160:161], v75 offset1:32
	ds_read2_b32 v[162:163], v73 offset1:32
	ds_read2_b32 v[164:165], v71 offset1:32
	ds_read2_b32 v[166:167], v69 offset1:32
	ds_read2_b32 v[168:169], v81 offset1:32
	ds_read2_b32 v[102:103], v79 offset0:64 offset1:96
	ds_read2_b32 v[26:27], v77 offset0:64 offset1:96
	global_load_dwordx4 v[20:23], v[16:17], off nt
	s_nop 0
	global_load_dwordx4 v[16:19], v[18:19], off nt
	s_waitcnt lgkmcnt(10)
	v_mov_b32_e32 v174, v105
	s_waitcnt lgkmcnt(8)
	v_mov_b32_e32 v176, v157
	s_waitcnt lgkmcnt(7)
	v_mov_b32_e32 v178, v159
	s_waitcnt lgkmcnt(6)
	v_mov_b32_e32 v180, v161
	s_waitcnt lgkmcnt(5)
	v_mov_b32_e32 v182, v163
	s_waitcnt lgkmcnt(4)
	v_mov_b32_e32 v184, v165
	s_waitcnt lgkmcnt(3)
	v_mov_b32_e32 v186, v167
	s_waitcnt lgkmcnt(2)
	v_mov_b32_e32 v188, v169
	v_add_u32_e32 v87, 0x800, v126
	v_add_u32_e32 v89, 0x1800, v126
	v_add_u32_e32 v91, 0x2800, v126
	v_add_u32_e32 v93, 0x3800, v126
	v_mov_b32_e32 v83, v29
	v_mov_b32_e32 v85, v29
	v_mov_b32_e32 v95, v29
	v_mov_b32_e32 v97, v29
	v_mov_b32_e32 v99, v29
	s_mov_b32 s10, 0
	s_waitcnt vmcnt(5)
	v_pk_fma_f32 v[190:191], v[2:3], v[104:105], 0 op_sel_hi:[1,0,0]
	v_pk_fma_f32 v[104:105], v[0:1], v[104:105], 0 op_sel_hi:[1,0,0]
	v_pk_fma_f32 v[192:193], v[2:3], v[156:157], 0 op_sel_hi:[1,0,0]
	v_pk_fma_f32 v[156:157], v[0:1], v[156:157], 0 op_sel_hi:[1,0,0]
	v_pk_fma_f32 v[194:195], v[2:3], v[158:159], 0 op_sel_hi:[1,0,0]
	v_pk_fma_f32 v[158:159], v[0:1], v[158:159], 0 op_sel_hi:[1,0,0]
	v_pk_fma_f32 v[196:197], v[2:3], v[160:161], 0 op_sel_hi:[1,0,0]
	v_pk_fma_f32 v[160:161], v[0:1], v[160:161], 0 op_sel_hi:[1,0,0]
	v_pk_fma_f32 v[198:199], v[2:3], v[162:163], 0 op_sel_hi:[1,0,0]
	v_pk_fma_f32 v[162:163], v[0:1], v[162:163], 0 op_sel_hi:[1,0,0]
	v_pk_fma_f32 v[200:201], v[2:3], v[164:165], 0 op_sel_hi:[1,0,0]
	v_pk_fma_f32 v[164:165], v[0:1], v[164:165], 0 op_sel_hi:[1,0,0]
	v_pk_fma_f32 v[202:203], v[2:3], v[166:167], 0 op_sel_hi:[1,0,0]
	v_pk_fma_f32 v[166:167], v[0:1], v[166:167], 0 op_sel_hi:[1,0,0]
	v_pk_fma_f32 v[2:3], v[2:3], v[168:169], 0 op_sel_hi:[1,0,0]
	v_pk_fma_f32 v[0:1], v[0:1], v[168:169], 0 op_sel_hi:[1,0,0]
	s_waitcnt vmcnt(4)
	v_pk_fma_f32 v[168:169], v[14:15], v[174:175], v[190:191] op_sel_hi:[1,0,1]
	v_pk_fma_f32 v[104:105], v[12:13], v[174:175], v[104:105] op_sel_hi:[1,0,1]
	v_pk_fma_f32 v[174:175], v[14:15], v[176:177], v[192:193] op_sel_hi:[1,0,1]
	v_pk_fma_f32 v[156:157], v[12:13], v[176:177], v[156:157] op_sel_hi:[1,0,1]
	v_pk_fma_f32 v[176:177], v[14:15], v[178:179], v[194:195] op_sel_hi:[1,0,1]
	v_pk_fma_f32 v[158:159], v[12:13], v[178:179], v[158:159] op_sel_hi:[1,0,1]
	v_pk_fma_f32 v[178:179], v[14:15], v[180:181], v[196:197] op_sel_hi:[1,0,1]
	v_pk_fma_f32 v[160:161], v[12:13], v[180:181], v[160:161] op_sel_hi:[1,0,1]
	v_pk_fma_f32 v[180:181], v[14:15], v[182:183], v[198:199] op_sel_hi:[1,0,1]
	v_pk_fma_f32 v[162:163], v[12:13], v[182:183], v[162:163] op_sel_hi:[1,0,1]
	v_pk_fma_f32 v[182:183], v[14:15], v[184:185], v[200:201] op_sel_hi:[1,0,1]
	v_pk_fma_f32 v[164:165], v[12:13], v[184:185], v[164:165] op_sel_hi:[1,0,1]
	v_pk_fma_f32 v[184:185], v[14:15], v[186:187], v[202:203] op_sel_hi:[1,0,1]
	v_pk_fma_f32 v[166:167], v[12:13], v[186:187], v[166:167] op_sel_hi:[1,0,1]
	v_pk_fma_f32 v[2:3], v[14:15], v[188:189], v[2:3] op_sel_hi:[1,0,1]
	v_pk_fma_f32 v[0:1], v[12:13], v[188:189], v[0:1] op_sel_hi:[1,0,1]
	ds_read2_b32 v[186:187], v75 offset0:64 offset1:96
	ds_read2_b32 v[188:189], v73 offset0:64 offset1:96
	ds_read2_b32 v[190:191], v71 offset0:64 offset1:96
	ds_read2_b32 v[192:193], v69 offset0:64 offset1:96
	ds_read2_b32 v[194:195], v81 offset0:64 offset1:96
	s_waitcnt vmcnt(3)
	v_pk_fma_f32 v[168:169], v[6:7], v[24:25], v[168:169] op_sel_hi:[1,0,1]
	v_pk_fma_f32 v[104:105], v[4:5], v[24:25], v[104:105] op_sel_hi:[1,0,1]
	s_waitcnt lgkmcnt(6)
; __device__ __forceinline__ void p0_mod_item(const Params& p, LAS unsigned char* lds, int item) {
;     ...
;     for (int pass = 0; pass < 32; ++pass) { const int i = pass * 32 + rs; const f32x4 w = *(const f32x4*)(p.w_ada + (size_t)i * NMOD + j0 + 4 * l16);
; #pragma unroll
;         for (int b = 0; b < 8; ++b) acc[b] += cs[b * DM + i] * w; }
	v_pk_fma_f32 v[156:157], v[4:5], v[102:103], v[156:157] op_sel_hi:[1,0,1]
	s_waitcnt lgkmcnt(5)
	v_pk_fma_f32 v[158:159], v[4:5], v[26:27], v[158:159] op_sel_hi:[1,0,1]
	s_waitcnt lgkmcnt(4)
	v_pk_fma_f32 v[160:161], v[4:5], v[186:187], v[160:161] op_sel_hi:[1,0,1]
	s_waitcnt lgkmcnt(3)
	v_pk_fma_f32 v[162:163], v[4:5], v[188:189], v[162:163] op_sel_hi:[1,0,1]
	s_waitcnt lgkmcnt(2)
	v_pk_fma_f32 v[164:165], v[4:5], v[190:191], v[164:165] op_sel_hi:[1,0,1]
	s_waitcnt lgkmcnt(1)
	v_pk_fma_f32 v[166:167], v[4:5], v[192:193], v[166:167] op_sel_hi:[1,0,1]
	s_waitcnt lgkmcnt(0)
	v_pk_fma_f32 v[0:1], v[4:5], v[194:195], v[0:1] op_sel_hi:[1,0,1]
	v_mov_b32_e32 v4, v25
	v_pk_fma_f32 v[174:175], v[6:7], v[102:103], v[174:175] op_sel_hi:[1,0,1]
	s_waitcnt vmcnt(2)
	v_pk_fma_f32 v[24:25], v[10:11], v[4:5], v[168:169] op_sel_hi:[1,0,1]
	v_pk_fma_f32 v[104:105], v[8:9], v[4:5], v[104:105] op_sel_hi:[1,0,1]
	v_mov_b32_e32 v4, v103
	v_pk_fma_f32 v[176:177], v[6:7], v[26:27], v[176:177] op_sel_hi:[1,0,1]
	v_pk_fma_f32 v[102:103], v[10:11], v[4:5], v[174:175] op_sel_hi:[1,0,1]
	v_pk_fma_f32 v[156:157], v[8:9], v[4:5], v[156:157] op_sel_hi:[1,0,1]
	v_mov_b32_e32 v4, v27
	v_pk_fma_f32 v[178:179], v[6:7], v[186:187], v[178:179] op_sel_hi:[1,0,1]
	v_pk_fma_f32 v[26:27], v[10:11], v[4:5], v[176:177] op_sel_hi:[1,0,1]
	v_pk_fma_f32 v[158:159], v[8:9], v[4:5], v[158:159] op_sel_hi:[1,0,1]
	v_mov_b32_e32 v4, v187
	v_pk_fma_f32 v[180:181], v[6:7], v[188:189], v[180:181] op_sel_hi:[1,0,1]
	v_pk_fma_f32 v[168:169], v[10:11], v[4:5], v[178:179] op_sel_hi:[1,0,1]
	v_pk_fma_f32 v[160:161], v[8:9], v[4:5], v[160:161] op_sel_hi:[1,0,1]
	v_mov_b32_e32 v4, v189
	v_pk_fma_f32 v[182:183], v[6:7], v[190:191], v[182:183] op_sel_hi:[1,0,1]
	v_pk_fma_f32 v[174:175], v[10:11], v[4:5], v[180:181] op_sel_hi:[1,0,1]
	v_pk_fma_f32 v[162:163], v[8:9], v[4:5], v[162:163] op_sel_hi:[1,0,1]
	v_mov_b32_e32 v4, v191
	v_pk_fma_f32 v[184:185], v[6:7], v[192:193], v[184:185] op_sel_hi:[1,0,1]
	v_pk_fma_f32 v[2:3], v[6:7], v[194:195], v[2:3] op_sel_hi:[1,0,1]
	v_lshl_add_u64 v[6:7], v[100:101], 0, v[50:51]
	v_pk_fma_f32 v[176:177], v[10:11], v[4:5], v[182:183] op_sel_hi:[1,0,1]
	v_pk_fma_f32 v[164:165], v[8:9], v[4:5], v[164:165] op_sel_hi:[1,0,1]
	v_mov_b32_e32 v4, v193
	global_load_dwordx4 v[12:15], v[6:7], off nt
	v_pk_fma_f32 v[178:179], v[10:11], v[4:5], v[184:185] op_sel_hi:[1,0,1]
	v_pk_fma_f32 v[166:167], v[8:9], v[4:5], v[166:167] op_sel_hi:[1,0,1]
	v_lshl_add_u64 v[4:5], v[100:101], 0, v[52:53]
	global_load_dwordx4 v[4:7], v[4:5], off nt
	v_mov_b32_e32 v182, v195
	ds_read2_b32 v[180:181], v126 offset0:128 offset1:160
	v_pk_fma_f32 v[2:3], v[10:11], v[182:183], v[2:3] op_sel_hi:[1,0,1]
	ds_read2_b32 v[184:185], v79 offset0:128 offset1:160
	v_pk_fma_f32 v[0:1], v[8:9], v[182:183], v[0:1] op_sel_hi:[1,0,1]
	ds_read2_b32 v[182:183], v77 offset0:128 offset1:160
	ds_read2_b32 v[186:187], v75 offset0:128 offset1:160
	ds_read2_b32 v[188:189], v73 offset0:128 offset1:160
	ds_read2_b32 v[190:191], v71 offset0:128 offset1:160
	ds_read2_b32 v[192:193], v69 offset0:128 offset1:160
	ds_read2_b32 v[194:195], v81 offset0:128 offset1:160
	s_waitcnt vmcnt(3) lgkmcnt(7)
	v_pk_fma_f32 v[24:25], v[22:23], v[180:181], v[24:25] op_sel_hi:[1,0,1]
	v_pk_fma_f32 v[104:105], v[20:21], v[180:181], v[104:105] op_sel_hi:[1,0,1]
	s_waitcnt lgkmcnt(6)
	v_pk_fma_f32 v[156:157], v[20:21], v[184:185], v[156:157] op_sel_hi:[1,0,1]
	s_waitcnt lgkmcnt(5)
	v_pk_fma_f32 v[158:159], v[20:21], v[182:183], v[158:159] op_sel_hi:[1,0,1]
	s_waitcnt lgkmcnt(4)
	v_pk_fma_f32 v[160:161], v[20:21], v[186:187], v[160:161] op_sel_hi:[1,0,1]
	s_waitcnt lgkmcnt(3)
	v_pk_fma_f32 v[162:163], v[20:21], v[188:189], v[162:163] op_sel_hi:[1,0,1]
	s_waitcnt lgkmcnt(2)
	v_pk_fma_f32 v[164:165], v[20:21], v[190:191], v[164:165] op_sel_hi:[1,0,1]
	s_waitcnt lgkmcnt(1)
	v_pk_fma_f32 v[166:167], v[20:21], v[192:193], v[166:167] op_sel_hi:[1,0,1]
	s_waitcnt lgkmcnt(0)
	v_pk_fma_f32 v[0:1], v[20:21], v[194:195], v[0:1] op_sel_hi:[1,0,1]
	v_mov_b32_e32 v20, v181
	v_lshl_add_u64 v[8:9], v[100:101], 0, v[54:55]
	v_pk_fma_f32 v[102:103], v[22:23], v[184:185], v[102:103] op_sel_hi:[1,0,1]
	v_pk_fma_f32 v[26:27], v[22:23], v[182:183], v[26:27] op_sel_hi:[1,0,1]
	v_pk_fma_f32 v[168:169], v[22:23], v[186:187], v[168:169] op_sel_hi:[1,0,1]
	v_pk_fma_f32 v[174:175], v[22:23], v[188:189], v[174:175] op_sel_hi:[1,0,1]
	v_pk_fma_f32 v[176:177], v[22:23], v[190:191], v[176:177] op_sel_hi:[1,0,1]
	v_pk_fma_f32 v[178:179], v[22:23], v[192:193], v[178:179] op_sel_hi:[1,0,1]
	v_pk_fma_f32 v[2:3], v[22:23], v[194:195], v[2:3] op_sel_hi:[1,0,1]
	global_load_dwordx4 v[8:11], v[8:9], off nt
	s_waitcnt vmcnt(3)
; __device__ __forceinline__ void p0_mod_item(const Params& p, LAS unsigned char* lds, int item) {
;     ...
;     for (int pass = 0; pass < 32; ++pass) { const int i = pass * 32 + rs; const f32x4 w = *(const f32x4*)(p.w_ada + (size_t)i * NMOD + j0 + 4 * l16);
; #pragma unroll
;         for (int b = 0; b < 8; ++b) acc[b] += cs[b * DM + i] * w; }
	v_pk_fma_f32 v[22:23], v[18:19], v[20:21], v[24:25] op_sel_hi:[1,0,1]
	v_mov_b32_e32 v24, v185
	v_pk_fma_f32 v[20:21], v[16:17], v[20:21], v[104:105] op_sel_hi:[1,0,1]
	v_pk_fma_f32 v[102:103], v[18:19], v[24:25], v[102:103] op_sel_hi:[1,0,1]
	v_pk_fma_f32 v[24:25], v[16:17], v[24:25], v[156:157] op_sel_hi:[1,0,1]
	v_mov_b32_e32 v104, v183
	v_mov_b32_e32 v156, v187
	v_pk_fma_f32 v[26:27], v[18:19], v[104:105], v[26:27] op_sel_hi:[1,0,1]
	v_pk_fma_f32 v[104:105], v[16:17], v[104:105], v[158:159] op_sel_hi:[1,0,1]
	v_pk_fma_f32 v[158:159], v[18:19], v[156:157], v[168:169] op_sel_hi:[1,0,1]
	v_pk_fma_f32 v[156:157], v[16:17], v[156:157], v[160:161] op_sel_hi:[1,0,1]
	v_mov_b32_e32 v160, v189
	v_pk_fma_f32 v[168:169], v[18:19], v[160:161], v[174:175] op_sel_hi:[1,0,1]
	v_pk_fma_f32 v[160:161], v[16:17], v[160:161], v[162:163] op_sel_hi:[1,0,1]
	v_mov_b32_e32 v162, v191
	v_pk_fma_f32 v[174:175], v[18:19], v[162:163], v[176:177] op_sel_hi:[1,0,1]
	v_pk_fma_f32 v[162:163], v[16:17], v[162:163], v[164:165] op_sel_hi:[1,0,1]
	v_mov_b32_e32 v164, v193
	v_pk_fma_f32 v[176:177], v[18:19], v[164:165], v[178:179] op_sel_hi:[1,0,1]
	v_mov_b32_e32 v178, v195
	v_pk_fma_f32 v[164:165], v[16:17], v[164:165], v[166:167] op_sel_hi:[1,0,1]
	v_pk_fma_f32 v[16:17], v[16:17], v[178:179], v[0:1] op_sel_hi:[1,0,1]
	v_lshl_add_u64 v[0:1], v[100:101], 0, v[56:57]
	v_pk_fma_f32 v[18:19], v[18:19], v[178:179], v[2:3] op_sel_hi:[1,0,1]
	global_load_dwordx4 v[0:3], v[0:1], off nt
	ds_read2_b32 v[166:167], v126 offset0:192 offset1:224
	ds_read2_b32 v[180:181], v79 offset0:192 offset1:224
	ds_read2_b32 v[178:179], v77 offset0:192 offset1:224
	ds_read2_b32 v[182:183], v75 offset0:192 offset1:224
	ds_read2_b32 v[184:185], v73 offset0:192 offset1:224
	ds_read2_b32 v[186:187], v71 offset0:192 offset1:224
	ds_read2_b32 v[188:189], v69 offset0:192 offset1:224
	ds_read2_b32 v[190:191], v81 offset0:192 offset1:224
	v_add_u32_e32 v71, 0x2400, v126
	v_add_u32_e32 v73, 0x3400, v126
	v_mov_b32_e32 v69, v29
	v_mov_b32_e32 v75, v29
	v_mov_b32_e32 v77, v29
	v_mov_b32_e32 v79, v29
	v_mov_b32_e32 v81, v29
	s_waitcnt vmcnt(3) lgkmcnt(7)
	v_pk_fma_f32 v[22:23], v[14:15], v[166:167], v[22:23] op_sel_hi:[1,0,1]
	v_pk_fma_f32 v[20:21], v[12:13], v[166:167], v[20:21] op_sel_hi:[1,0,1]
	s_waitcnt lgkmcnt(6)
	v_pk_fma_f32 v[102:103], v[14:15], v[180:181], v[102:103] op_sel_hi:[1,0,1]
	s_waitcnt lgkmcnt(5)
	v_pk_fma_f32 v[26:27], v[14:15], v[178:179], v[26:27] op_sel_hi:[1,0,1]
	s_waitcnt lgkmcnt(4)
	v_pk_fma_f32 v[158:159], v[14:15], v[182:183], v[158:159] op_sel_hi:[1,0,1]
	s_waitcnt lgkmcnt(3)
	v_pk_fma_f32 v[168:169], v[14:15], v[184:185], v[168:169] op_sel_hi:[1,0,1]
	s_waitcnt lgkmcnt(2)
	v_pk_fma_f32 v[174:175], v[14:15], v[186:187], v[174:175] op_sel_hi:[1,0,1]
	s_waitcnt lgkmcnt(1)
	v_pk_fma_f32 v[176:177], v[14:15], v[188:189], v[176:177] op_sel_hi:[1,0,1]
	s_waitcnt lgkmcnt(0)
	v_pk_fma_f32 v[18:19], v[14:15], v[190:191], v[18:19] op_sel_hi:[1,0,1]
	v_mov_b32_e32 v14, v167
	v_pk_fma_f32 v[24:25], v[12:13], v[180:181], v[24:25] op_sel_hi:[1,0,1]
	s_waitcnt vmcnt(2)
	v_pk_fma_f32 v[22:23], v[6:7], v[14:15], v[22:23] op_sel_hi:[1,0,1]
	v_pk_fma_f32 v[20:21], v[4:5], v[14:15], v[20:21] op_sel_hi:[1,0,1]
	v_mov_b32_e32 v14, v181
	v_pk_fma_f32 v[104:105], v[12:13], v[178:179], v[104:105] op_sel_hi:[1,0,1]
	v_pk_fma_f32 v[102:103], v[6:7], v[14:15], v[102:103] op_sel_hi:[1,0,1]
	v_pk_fma_f32 v[24:25], v[4:5], v[14:15], v[24:25] op_sel_hi:[1,0,1]
	v_mov_b32_e32 v14, v179
	v_pk_fma_f32 v[166:167], v[6:7], v[14:15], v[26:27] op_sel_hi:[1,0,1]
	v_pk_fma_f32 v[104:105], v[4:5], v[14:15], v[104:105] op_sel_hi:[1,0,1]
	v_lshl_add_u64 v[14:15], v[100:101], 0, v[58:59]
	v_pk_fma_f32 v[156:157], v[12:13], v[182:183], v[156:157] op_sel_hi:[1,0,1]
	v_pk_fma_f32 v[160:161], v[12:13], v[184:185], v[160:161] op_sel_hi:[1,0,1]
	v_pk_fma_f32 v[162:163], v[12:13], v[186:187], v[162:163] op_sel_hi:[1,0,1]
	v_pk_fma_f32 v[164:165], v[12:13], v[188:189], v[164:165] op_sel_hi:[1,0,1]
	v_pk_fma_f32 v[12:13], v[12:13], v[190:191], v[16:17] op_sel_hi:[1,0,1]
	global_load_dwordx4 v[14:17], v[14:15], off nt
	v_mov_b32_e32 v26, v183
	v_pk_fma_f32 v[158:159], v[6:7], v[26:27], v[158:159] op_sel_hi:[1,0,1]
	v_pk_fma_f32 v[156:157], v[4:5], v[26:27], v[156:157] op_sel_hi:[1,0,1]
	v_mov_b32_e32 v26, v185
	v_pk_fma_f32 v[168:169], v[6:7], v[26:27], v[168:169] op_sel_hi:[1,0,1]
	v_pk_fma_f32 v[160:161], v[4:5], v[26:27], v[160:161] op_sel_hi:[1,0,1]
	v_mov_b32_e32 v26, v187
	v_pk_fma_f32 v[174:175], v[6:7], v[26:27], v[174:175] op_sel_hi:[1,0,1]
	v_pk_fma_f32 v[162:163], v[4:5], v[26:27], v[162:163] op_sel_hi:[1,0,1]
	v_mov_b32_e32 v26, v189
	v_pk_fma_f32 v[176:177], v[6:7], v[26:27], v[176:177] op_sel_hi:[1,0,1]
	v_pk_fma_f32 v[164:165], v[4:5], v[26:27], v[164:165] op_sel_hi:[1,0,1]
	v_add_u32_e32 v27, 0x1400, v126
	v_add_u32_e32 v26, 0x400, v126
	ds_read2_b32 v[182:183], v27 offset1:32
	ds_read2_b32 v[180:181], v26 offset1:32
	v_mov_b32_e32 v178, v191
	v_pk_fma_f32 v[12:13], v[4:5], v[178:179], v[12:13] op_sel_hi:[1,0,1]
	v_lshl_add_u64 v[4:5], v[100:101], 0, v[60:61]
	v_pk_fma_f32 v[18:19], v[6:7], v[178:179], v[18:19] op_sel_hi:[1,0,1]
	global_load_dwordx4 v[4:7], v[4:5], off nt
	s_waitcnt vmcnt(3) lgkmcnt(1)
	v_pk_fma_f32 v[184:185], v[8:9], v[182:183], v[24:25] op_sel_hi:[1,0,1]
	v_add_u32_e32 v25, 0x7400, v126
	s_waitcnt lgkmcnt(0)
	v_pk_fma_f32 v[178:179], v[10:11], v[180:181], v[22:23] op_sel_hi:[1,0,1]
	v_add_u32_e32 v22, 0x4400, v126
	v_add_u32_e32 v23, 0x5400, v126
	v_add_u32_e32 v24, 0x6400, v126
	ds_read2_b32 v[196:197], v25 offset1:32
	ds_read2_b32 v[186:187], v71 offset1:32
	ds_read2_b32 v[188:189], v73 offset1:32
	ds_read2_b32 v[190:191], v22 offset1:32
	ds_read2_b32 v[192:193], v23 offset1:32
	ds_read2_b32 v[194:195], v24 offset1:32
	v_pk_fma_f32 v[20:21], v[8:9], v[180:181], v[20:21] op_sel_hi:[1,0,1]
	s_waitcnt lgkmcnt(5)
; __device__ __forceinline__ void p0_mod_item(const Params& p, LAS unsigned char* lds, int item) {
;     ...
;     for (int pass = 0; pass < 32; ++pass) { const int i = pass * 32 + rs; const f32x4 w = *(const f32x4*)(p.w_ada + (size_t)i * NMOD + j0 + 4 * l16);
; #pragma unroll
;         for (int b = 0; b < 8; ++b) acc[b] += cs[b * DM + i] * w; }
	v_pk_fma_f32 v[198:199], v[10:11], v[196:197], v[18:19] op_sel_hi:[1,0,1]
	v_mov_b32_e32 v18, v181
	v_pk_fma_f32 v[102:103], v[10:11], v[182:183], v[102:103] op_sel_hi:[1,0,1]
	s_waitcnt lgkmcnt(4)
	v_pk_fma_f32 v[166:167], v[10:11], v[186:187], v[166:167] op_sel_hi:[1,0,1]
	s_waitcnt lgkmcnt(3)
	v_pk_fma_f32 v[158:159], v[10:11], v[188:189], v[158:159] op_sel_hi:[1,0,1]
	s_waitcnt lgkmcnt(2)
	v_pk_fma_f32 v[168:169], v[10:11], v[190:191], v[168:169] op_sel_hi:[1,0,1]
	s_waitcnt lgkmcnt(1)
	v_pk_fma_f32 v[174:175], v[10:11], v[192:193], v[174:175] op_sel_hi:[1,0,1]
	s_waitcnt lgkmcnt(0)
	v_pk_fma_f32 v[176:177], v[10:11], v[194:195], v[176:177] op_sel_hi:[1,0,1]
	v_lshl_add_u64 v[10:11], v[100:101], 0, v[62:63]
	s_waitcnt vmcnt(2)
	v_pk_fma_f32 v[178:179], v[2:3], v[18:19], v[178:179] op_sel_hi:[1,0,1]
	v_pk_fma_f32 v[180:181], v[0:1], v[18:19], v[20:21] op_sel_hi:[1,0,1]
	v_mov_b32_e32 v18, v183
	v_pk_fma_f32 v[104:105], v[8:9], v[186:187], v[104:105] op_sel_hi:[1,0,1]
	v_pk_fma_f32 v[156:157], v[8:9], v[188:189], v[156:157] op_sel_hi:[1,0,1]
	v_pk_fma_f32 v[160:161], v[8:9], v[190:191], v[160:161] op_sel_hi:[1,0,1]
	v_pk_fma_f32 v[162:163], v[8:9], v[192:193], v[162:163] op_sel_hi:[1,0,1]
	v_pk_fma_f32 v[164:165], v[8:9], v[194:195], v[164:165] op_sel_hi:[1,0,1]
	v_pk_fma_f32 v[8:9], v[8:9], v[196:197], v[12:13] op_sel_hi:[1,0,1]
	global_load_dwordx4 v[10:13], v[10:11], off nt
	v_pk_fma_f32 v[102:103], v[2:3], v[18:19], v[102:103] op_sel_hi:[1,0,1]
	v_pk_fma_f32 v[182:183], v[0:1], v[18:19], v[184:185] op_sel_hi:[1,0,1]
	v_mov_b32_e32 v18, v187
	v_pk_fma_f32 v[166:167], v[2:3], v[18:19], v[166:167] op_sel_hi:[1,0,1]
	v_pk_fma_f32 v[104:105], v[0:1], v[18:19], v[104:105] op_sel_hi:[1,0,1]
	v_mov_b32_e32 v18, v189
	v_pk_fma_f32 v[158:159], v[2:3], v[18:19], v[158:159] op_sel_hi:[1,0,1]
	v_pk_fma_f32 v[156:157], v[0:1], v[18:19], v[156:157] op_sel_hi:[1,0,1]
	v_mov_b32_e32 v18, v191
	v_pk_fma_f32 v[168:169], v[2:3], v[18:19], v[168:169] op_sel_hi:[1,0,1]
	v_pk_fma_f32 v[160:161], v[0:1], v[18:19], v[160:161] op_sel_hi:[1,0,1]
	v_mov_b32_e32 v18, v193
	v_pk_fma_f32 v[174:175], v[2:3], v[18:19], v[174:175] op_sel_hi:[1,0,1]
	v_pk_fma_f32 v[162:163], v[0:1], v[18:19], v[162:163] op_sel_hi:[1,0,1]
	v_mov_b32_e32 v18, v195
	v_pk_fma_f32 v[176:177], v[2:3], v[18:19], v[176:177] op_sel_hi:[1,0,1]
	v_pk_fma_f32 v[164:165], v[0:1], v[18:19], v[164:165] op_sel_hi:[1,0,1]
	v_lshl_add_u64 v[18:19], v[100:101], 0, v[64:65]
	global_load_dwordx4 v[18:21], v[18:19], off nt
	ds_read2_b32 v[184:185], v26 offset0:64 offset1:96
	v_mov_b32_e32 v186, v197
	v_pk_fma_f32 v[2:3], v[2:3], v[186:187], v[198:199] op_sel_hi:[1,0,1]
	ds_read2_b32 v[188:189], v27 offset0:64 offset1:96
	v_pk_fma_f32 v[0:1], v[0:1], v[186:187], v[8:9] op_sel_hi:[1,0,1]
	ds_read2_b32 v[186:187], v73 offset0:64 offset1:96
	ds_read2_b32 v[190:191], v22 offset0:64 offset1:96
	s_waitcnt vmcnt(3) lgkmcnt(3)
	v_pk_fma_f32 v[8:9], v[16:17], v[184:185], v[178:179] op_sel_hi:[1,0,1]
	ds_read2_b32 v[178:179], v71 offset0:64 offset1:96
	ds_read2_b32 v[192:193], v23 offset0:64 offset1:96
	ds_read2_b32 v[194:195], v24 offset0:64 offset1:96
	ds_read2_b32 v[196:197], v25 offset0:64 offset1:96
	v_pk_fma_f32 v[180:181], v[14:15], v[184:185], v[180:181] op_sel_hi:[1,0,1]
	s_waitcnt lgkmcnt(6)
	v_pk_fma_f32 v[182:183], v[14:15], v[188:189], v[182:183] op_sel_hi:[1,0,1]
	s_waitcnt lgkmcnt(3)
	v_pk_fma_f32 v[104:105], v[14:15], v[178:179], v[104:105] op_sel_hi:[1,0,1]
	v_pk_fma_f32 v[156:157], v[14:15], v[186:187], v[156:157] op_sel_hi:[1,0,1]
	v_pk_fma_f32 v[160:161], v[14:15], v[190:191], v[160:161] op_sel_hi:[1,0,1]
	s_waitcnt lgkmcnt(2)
	v_pk_fma_f32 v[162:163], v[14:15], v[192:193], v[162:163] op_sel_hi:[1,0,1]
	s_waitcnt lgkmcnt(1)
	v_pk_fma_f32 v[164:165], v[14:15], v[194:195], v[164:165] op_sel_hi:[1,0,1]
	s_waitcnt lgkmcnt(0)
	v_pk_fma_f32 v[0:1], v[14:15], v[196:197], v[0:1] op_sel_hi:[1,0,1]
	v_lshl_add_u64 v[14:15], v[100:101], 0, v[66:67]
	v_pk_fma_f32 v[102:103], v[16:17], v[188:189], v[102:103] op_sel_hi:[1,0,1]
	v_pk_fma_f32 v[166:167], v[16:17], v[178:179], v[166:167] op_sel_hi:[1,0,1]
	v_pk_fma_f32 v[158:159], v[16:17], v[186:187], v[158:159] op_sel_hi:[1,0,1]
	v_pk_fma_f32 v[168:169], v[16:17], v[190:191], v[168:169] op_sel_hi:[1,0,1]
	v_pk_fma_f32 v[174:175], v[16:17], v[192:193], v[174:175] op_sel_hi:[1,0,1]
	v_pk_fma_f32 v[176:177], v[16:17], v[194:195], v[176:177] op_sel_hi:[1,0,1]
	v_pk_fma_f32 v[2:3], v[16:17], v[196:197], v[2:3] op_sel_hi:[1,0,1]
	global_load_dwordx4 v[14:17], v[14:15], off nt
	v_mov_b32_e32 v178, v185
	s_waitcnt vmcnt(3)
	v_pk_fma_f32 v[184:185], v[6:7], v[178:179], v[8:9] op_sel_hi:[1,0,1]
	v_mov_b32_e32 v8, v189
	v_pk_fma_f32 v[102:103], v[6:7], v[8:9], v[102:103] op_sel_hi:[1,0,1]
	v_pk_fma_f32 v[182:183], v[4:5], v[8:9], v[182:183] op_sel_hi:[1,0,1]
	v_mov_b32_e32 v8, v179
	v_pk_fma_f32 v[166:167], v[6:7], v[8:9], v[166:167] op_sel_hi:[1,0,1]
	v_pk_fma_f32 v[104:105], v[4:5], v[8:9], v[104:105] op_sel_hi:[1,0,1]
	v_mov_b32_e32 v8, v187
	ds_read2_b32 v[186:187], v26 offset0:128 offset1:160
	v_pk_fma_f32 v[158:159], v[6:7], v[8:9], v[158:159] op_sel_hi:[1,0,1]
	v_pk_fma_f32 v[156:157], v[4:5], v[8:9], v[156:157] op_sel_hi:[1,0,1]
	v_mov_b32_e32 v8, v191
	v_pk_fma_f32 v[168:169], v[6:7], v[8:9], v[168:169] op_sel_hi:[1,0,1]
	v_pk_fma_f32 v[160:161], v[4:5], v[8:9], v[160:161] op_sel_hi:[1,0,1]
	v_mov_b32_e32 v8, v193
	v_pk_fma_f32 v[180:181], v[4:5], v[178:179], v[180:181] op_sel_hi:[1,0,1]
	v_pk_fma_f32 v[174:175], v[6:7], v[8:9], v[174:175] op_sel_hi:[1,0,1]
	v_pk_fma_f32 v[162:163], v[4:5], v[8:9], v[162:163] op_sel_hi:[1,0,1]
	v_mov_b32_e32 v8, v195
	v_mov_b32_e32 v178, v197
	v_pk_fma_f32 v[176:177], v[6:7], v[8:9], v[176:177] op_sel_hi:[1,0,1]
	v_pk_fma_f32 v[2:3], v[6:7], v[178:179], v[2:3] op_sel_hi:[1,0,1]
	v_lshl_add_u64 v[6:7], v[100:101], 0, v[28:29]
	v_pk_fma_f32 v[164:165], v[4:5], v[8:9], v[164:165] op_sel_hi:[1,0,1]
	global_load_dwordx4 v[6:9], v[6:7], off nt
	ds_read2_b32 v[188:189], v27 offset0:128 offset1:160
	v_pk_fma_f32 v[0:1], v[4:5], v[178:179], v[0:1] op_sel_hi:[1,0,1]
	ds_read2_b32 v[178:179], v71 offset0:128 offset1:160
	ds_read2_b32 v[190:191], v22 offset0:128 offset1:160
	ds_read2_b32 v[192:193], v23 offset0:128 offset1:160
	s_waitcnt vmcnt(3) lgkmcnt(4)
; __device__ __forceinline__ void p0_mod_item(const Params& p, LAS unsigned char* lds, int item) {
;     ...
;     for (int pass = 0; pass < 32; ++pass) { const int i = pass * 32 + rs; const f32x4 w = *(const f32x4*)(p.w_ada + (size_t)i * NMOD + j0 + 4 * l16);
; #pragma unroll
;         for (int b = 0; b < 8; ++b) acc[b] += cs[b * DM + i] * w; }
	v_pk_fma_f32 v[4:5], v[12:13], v[186:187], v[184:185] op_sel_hi:[1,0,1]
	ds_read2_b32 v[184:185], v73 offset0:128 offset1:160
	ds_read2_b32 v[194:195], v24 offset0:128 offset1:160
	ds_read2_b32 v[196:197], v25 offset0:128 offset1:160
	v_pk_fma_f32 v[180:181], v[10:11], v[186:187], v[180:181] op_sel_hi:[1,0,1]
	s_waitcnt lgkmcnt(6)
	v_pk_fma_f32 v[182:183], v[10:11], v[188:189], v[182:183] op_sel_hi:[1,0,1]
	s_waitcnt lgkmcnt(5)
	v_pk_fma_f32 v[104:105], v[10:11], v[178:179], v[104:105] op_sel_hi:[1,0,1]
	s_waitcnt lgkmcnt(2)
	v_pk_fma_f32 v[156:157], v[10:11], v[184:185], v[156:157] op_sel_hi:[1,0,1]
	v_pk_fma_f32 v[160:161], v[10:11], v[190:191], v[160:161] op_sel_hi:[1,0,1]
	v_pk_fma_f32 v[162:163], v[10:11], v[192:193], v[162:163] op_sel_hi:[1,0,1]
	s_waitcnt lgkmcnt(1)
	v_pk_fma_f32 v[164:165], v[10:11], v[194:195], v[164:165] op_sel_hi:[1,0,1]
	s_waitcnt lgkmcnt(0)
	v_pk_fma_f32 v[0:1], v[10:11], v[196:197], v[0:1] op_sel_hi:[1,0,1]
	v_mov_b32_e32 v10, v187
	v_pk_fma_f32 v[102:103], v[12:13], v[188:189], v[102:103] op_sel_hi:[1,0,1]
	v_pk_fma_f32 v[166:167], v[12:13], v[178:179], v[166:167] op_sel_hi:[1,0,1]
	v_pk_fma_f32 v[158:159], v[12:13], v[184:185], v[158:159] op_sel_hi:[1,0,1]
	v_pk_fma_f32 v[168:169], v[12:13], v[190:191], v[168:169] op_sel_hi:[1,0,1]
	v_pk_fma_f32 v[174:175], v[12:13], v[192:193], v[174:175] op_sel_hi:[1,0,1]
	v_pk_fma_f32 v[176:177], v[12:13], v[194:195], v[176:177] op_sel_hi:[1,0,1]
	s_waitcnt vmcnt(2)
	v_pk_fma_f32 v[4:5], v[20:21], v[10:11], v[4:5] op_sel_hi:[1,0,1]
	v_pk_fma_f32 v[180:181], v[18:19], v[10:11], v[180:181] op_sel_hi:[1,0,1]
	v_lshl_add_u64 v[10:11], v[100:101], 0, v[68:69]
	v_pk_fma_f32 v[2:3], v[12:13], v[196:197], v[2:3] op_sel_hi:[1,0,1]
	global_load_dwordx4 v[10:13], v[10:11], off nt
	v_mov_b32_e32 v178, v189
	v_pk_fma_f32 v[102:103], v[20:21], v[178:179], v[102:103] op_sel_hi:[1,0,1]
	v_pk_fma_f32 v[182:183], v[18:19], v[178:179], v[182:183] op_sel_hi:[1,0,1]
	v_mov_b32_e32 v178, v179
	v_pk_fma_f32 v[166:167], v[20:21], v[178:179], v[166:167] op_sel_hi:[1,0,1]
	v_pk_fma_f32 v[104:105], v[18:19], v[178:179], v[104:105] op_sel_hi:[1,0,1]
	v_mov_b32_e32 v178, v185
	v_pk_fma_f32 v[158:159], v[20:21], v[178:179], v[158:159] op_sel_hi:[1,0,1]
	v_pk_fma_f32 v[156:157], v[18:19], v[178:179], v[156:157] op_sel_hi:[1,0,1]
	v_mov_b32_e32 v178, v191
	v_pk_fma_f32 v[168:169], v[20:21], v[178:179], v[168:169] op_sel_hi:[1,0,1]
	v_pk_fma_f32 v[160:161], v[18:19], v[178:179], v[160:161] op_sel_hi:[1,0,1]
	v_mov_b32_e32 v178, v193
	v_pk_fma_f32 v[174:175], v[20:21], v[178:179], v[174:175] op_sel_hi:[1,0,1]
	v_pk_fma_f32 v[162:163], v[18:19], v[178:179], v[162:163] op_sel_hi:[1,0,1]
	v_mov_b32_e32 v178, v195
	v_pk_fma_f32 v[176:177], v[20:21], v[178:179], v[176:177] op_sel_hi:[1,0,1]
	v_pk_fma_f32 v[164:165], v[18:19], v[178:179], v[164:165] op_sel_hi:[1,0,1]
	ds_read2_b32 v[178:179], v26 offset0:192 offset1:224
	ds_read2_b32 v[184:185], v27 offset0:192 offset1:224
	v_mov_b32_e32 v26, v197
	v_pk_fma_f32 v[20:21], v[20:21], v[26:27], v[2:3] op_sel_hi:[1,0,1]
	v_pk_fma_f32 v[18:19], v[18:19], v[26:27], v[0:1] op_sel_hi:[1,0,1]
	v_add_u32_e32 v69, 0x4800, v126
	s_waitcnt vmcnt(2) lgkmcnt(1)
	v_pk_fma_f32 v[26:27], v[14:15], v[178:179], v[180:181] op_sel_hi:[1,0,1]
	s_waitcnt lgkmcnt(0)
	v_pk_fma_f32 v[180:181], v[14:15], v[184:185], v[182:183] op_sel_hi:[1,0,1]
	ds_read2_b32 v[182:183], v71 offset0:192 offset1:224
	ds_read2_b32 v[186:187], v73 offset0:192 offset1:224
	v_mov_b32_e32 v71, v29
	v_lshl_add_u64 v[0:1], v[100:101], 0, v[70:71]
	global_load_dwordx4 v[0:3], v[0:1], off nt
	ds_read2_b32 v[188:189], v22 offset0:192 offset1:224
	ds_read2_b32 v[22:23], v23 offset0:192 offset1:224
	ds_read2_b32 v[190:191], v24 offset0:192 offset1:224
	ds_read2_b32 v[24:25], v25 offset0:192 offset1:224
	v_pk_fma_f32 v[4:5], v[16:17], v[178:179], v[4:5] op_sel_hi:[1,0,1]
	s_waitcnt lgkmcnt(3)
	v_pk_fma_f32 v[168:169], v[16:17], v[188:189], v[168:169] op_sel_hi:[1,0,1]
	v_pk_fma_f32 v[160:161], v[14:15], v[188:189], v[160:161] op_sel_hi:[1,0,1]
	s_waitcnt lgkmcnt(2)
	v_pk_fma_f32 v[174:175], v[16:17], v[22:23], v[174:175] op_sel_hi:[1,0,1]
	v_pk_fma_f32 v[162:163], v[14:15], v[22:23], v[162:163] op_sel_hi:[1,0,1]
	v_mov_b32_e32 v22, v189
	s_waitcnt lgkmcnt(1)
	v_pk_fma_f32 v[176:177], v[16:17], v[190:191], v[176:177] op_sel_hi:[1,0,1]
	s_waitcnt lgkmcnt(0)
	v_pk_fma_f32 v[20:21], v[16:17], v[24:25], v[20:21] op_sel_hi:[1,0,1]
	v_pk_fma_f32 v[18:19], v[14:15], v[24:25], v[18:19] op_sel_hi:[1,0,1]
	v_mov_b32_e32 v24, v191
	v_pk_fma_f32 v[104:105], v[14:15], v[182:183], v[104:105] op_sel_hi:[1,0,1]
	v_pk_fma_f32 v[156:157], v[14:15], v[186:187], v[156:157] op_sel_hi:[1,0,1]
	v_pk_fma_f32 v[164:165], v[14:15], v[190:191], v[164:165] op_sel_hi:[1,0,1]
	v_mov_b32_e32 v14, v179
	v_pk_fma_f32 v[102:103], v[16:17], v[184:185], v[102:103] op_sel_hi:[1,0,1]
	v_pk_fma_f32 v[166:167], v[16:17], v[182:183], v[166:167] op_sel_hi:[1,0,1]
	s_waitcnt vmcnt(2)
; __device__ __forceinline__ void p0_mod_item(const Params& p, LAS unsigned char* lds, int item) {
;     ...
;     for (int pass = 0; pass < 32; ++pass) { const int i = pass * 32 + rs; const f32x4 w = *(const f32x4*)(p.w_ada + (size_t)i * NMOD + j0 + 4 * l16);
; #pragma unroll
;         for (int b = 0; b < 8; ++b) acc[b] += cs[b * DM + i] * w; }
	v_pk_fma_f32 v[168:169], v[8:9], v[22:23], v[168:169] op_sel_hi:[1,0,1]
	v_pk_fma_f32 v[160:161], v[6:7], v[22:23], v[160:161] op_sel_hi:[1,0,1]
	v_mov_b32_e32 v22, v23
	v_pk_fma_f32 v[174:175], v[8:9], v[22:23], v[174:175] op_sel_hi:[1,0,1]
	v_pk_fma_f32 v[22:23], v[6:7], v[22:23], v[162:163] op_sel_hi:[1,0,1]
	v_pk_fma_f32 v[162:163], v[8:9], v[24:25], v[176:177] op_sel_hi:[1,0,1]
	ds_read2_b32 v[176:177], v87 offset1:32
	v_pk_fma_f32 v[4:5], v[8:9], v[14:15], v[4:5] op_sel_hi:[1,0,1]
	v_pk_fma_f32 v[26:27], v[6:7], v[14:15], v[26:27] op_sel_hi:[1,0,1]
	v_mov_b32_e32 v14, v185
	v_pk_fma_f32 v[102:103], v[8:9], v[14:15], v[102:103] op_sel_hi:[1,0,1]
	v_pk_fma_f32 v[178:179], v[6:7], v[14:15], v[180:181] op_sel_hi:[1,0,1]
	v_mov_b32_e32 v14, v183
	v_pk_fma_f32 v[158:159], v[16:17], v[186:187], v[158:159] op_sel_hi:[1,0,1]
	v_pk_fma_f32 v[166:167], v[8:9], v[14:15], v[166:167] op_sel_hi:[1,0,1]
	v_pk_fma_f32 v[104:105], v[6:7], v[14:15], v[104:105] op_sel_hi:[1,0,1]
	v_mov_b32_e32 v14, v187
	v_mov_b32_e32 v73, v29
	v_pk_fma_f32 v[158:159], v[8:9], v[14:15], v[158:159] op_sel_hi:[1,0,1]
	v_pk_fma_f32 v[156:157], v[6:7], v[14:15], v[156:157] op_sel_hi:[1,0,1]
	v_lshl_add_u64 v[14:15], v[100:101], 0, v[72:73]
	v_pk_fma_f32 v[164:165], v[6:7], v[24:25], v[164:165] op_sel_hi:[1,0,1]
	v_mov_b32_e32 v24, v25
	global_load_dwordx4 v[14:17], v[14:15], off nt
	v_pk_fma_f32 v[8:9], v[8:9], v[24:25], v[20:21] op_sel_hi:[1,0,1]
	v_pk_fma_f32 v[18:19], v[6:7], v[24:25], v[18:19] op_sel_hi:[1,0,1]
	v_add_u32_e32 v71, 0x5800, v126
	v_add_u32_e32 v73, 0x6800, v126
	ds_read2_b32 v[180:181], v89 offset1:32
	s_waitcnt vmcnt(2) lgkmcnt(1)
	v_pk_fma_f32 v[20:21], v[12:13], v[176:177], v[4:5] op_sel_hi:[1,0,1]
	v_lshl_add_u64 v[4:5], v[100:101], 0, v[74:75]
	global_load_dwordx4 v[4:7], v[4:5], off nt
	v_add_u32_e32 v75, 0x7800, v126
	ds_read2_b32 v[182:183], v91 offset1:32
	ds_read2_b32 v[184:185], v93 offset1:32
	ds_read2_b32 v[186:187], v69 offset1:32
	ds_read2_b32 v[188:189], v71 offset1:32
	ds_read2_b32 v[190:191], v73 offset1:32
	ds_read2_b32 v[192:193], v75 offset1:32
	s_waitcnt lgkmcnt(6)
	v_pk_fma_f32 v[102:103], v[12:13], v[180:181], v[102:103] op_sel_hi:[1,0,1]
	s_waitcnt lgkmcnt(5)
	v_pk_fma_f32 v[166:167], v[12:13], v[182:183], v[166:167] op_sel_hi:[1,0,1]
	s_waitcnt lgkmcnt(4)
	v_pk_fma_f32 v[158:159], v[12:13], v[184:185], v[158:159] op_sel_hi:[1,0,1]
	s_waitcnt lgkmcnt(3)
	v_pk_fma_f32 v[168:169], v[12:13], v[186:187], v[168:169] op_sel_hi:[1,0,1]
	s_waitcnt lgkmcnt(2)
	v_pk_fma_f32 v[174:175], v[12:13], v[188:189], v[174:175] op_sel_hi:[1,0,1]
	s_waitcnt lgkmcnt(1)
	v_pk_fma_f32 v[162:163], v[12:13], v[190:191], v[162:163] op_sel_hi:[1,0,1]
	s_waitcnt lgkmcnt(0)
	v_pk_fma_f32 v[8:9], v[12:13], v[192:193], v[8:9] op_sel_hi:[1,0,1]
	v_mov_b32_e32 v12, v177
	v_pk_fma_f32 v[24:25], v[10:11], v[176:177], v[26:27] op_sel_hi:[1,0,1]
	v_pk_fma_f32 v[178:179], v[10:11], v[180:181], v[178:179] op_sel_hi:[1,0,1]
	v_pk_fma_f32 v[104:105], v[10:11], v[182:183], v[104:105] op_sel_hi:[1,0,1]
	v_pk_fma_f32 v[156:157], v[10:11], v[184:185], v[156:157] op_sel_hi:[1,0,1]
	v_pk_fma_f32 v[160:161], v[10:11], v[186:187], v[160:161] op_sel_hi:[1,0,1]
	v_pk_fma_f32 v[22:23], v[10:11], v[188:189], v[22:23] op_sel_hi:[1,0,1]
	v_pk_fma_f32 v[164:165], v[10:11], v[190:191], v[164:165] op_sel_hi:[1,0,1]
	v_pk_fma_f32 v[10:11], v[10:11], v[192:193], v[18:19] op_sel_hi:[1,0,1]
	v_mov_b32_e32 v180, v193
	ds_read2_b32 v[192:193], v75 offset0:64 offset1:96
	s_waitcnt vmcnt(2)
	v_pk_fma_f32 v[18:19], v[2:3], v[12:13], v[20:21] op_sel_hi:[1,0,1]
	v_mov_b32_e32 v20, v181
	v_pk_fma_f32 v[102:103], v[2:3], v[20:21], v[102:103] op_sel_hi:[1,0,1]
	v_pk_fma_f32 v[176:177], v[0:1], v[20:21], v[178:179] op_sel_hi:[1,0,1]
	v_mov_b32_e32 v20, v183
	v_pk_fma_f32 v[166:167], v[2:3], v[20:21], v[166:167] op_sel_hi:[1,0,1]
	v_pk_fma_f32 v[104:105], v[0:1], v[20:21], v[104:105] op_sel_hi:[1,0,1]
	v_mov_b32_e32 v20, v185
	v_pk_fma_f32 v[158:159], v[2:3], v[20:21], v[158:159] op_sel_hi:[1,0,1]
	v_pk_fma_f32 v[156:157], v[0:1], v[20:21], v[156:157] op_sel_hi:[1,0,1]
	v_mov_b32_e32 v20, v187
	v_pk_fma_f32 v[168:169], v[2:3], v[20:21], v[168:169] op_sel_hi:[1,0,1]
	v_pk_fma_f32 v[160:161], v[0:1], v[20:21], v[160:161] op_sel_hi:[1,0,1]
	v_mov_b32_e32 v20, v189
	v_pk_fma_f32 v[12:13], v[0:1], v[12:13], v[24:25] op_sel_hi:[1,0,1]
	v_lshl_add_u64 v[24:25], v[100:101], 0, v[76:77]
	v_pk_fma_f32 v[174:175], v[2:3], v[20:21], v[174:175] op_sel_hi:[1,0,1]
	v_pk_fma_f32 v[178:179], v[0:1], v[20:21], v[22:23] op_sel_hi:[1,0,1]
	v_mov_b32_e32 v20, v191
	global_load_dwordx4 v[24:27], v[24:25], off nt
	v_pk_fma_f32 v[162:163], v[2:3], v[20:21], v[162:163] op_sel_hi:[1,0,1]
	v_pk_fma_f32 v[164:165], v[0:1], v[20:21], v[164:165] op_sel_hi:[1,0,1]
	v_lshl_add_u64 v[20:21], v[100:101], 0, v[78:79]
	global_load_dwordx4 v[20:23], v[20:21], off nt
	v_pk_fma_f32 v[2:3], v[2:3], v[180:181], v[8:9] op_sel_hi:[1,0,1]
	ds_read2_b32 v[8:9], v87 offset0:64 offset1:96
	ds_read2_b32 v[182:183], v89 offset0:64 offset1:96
	v_pk_fma_f32 v[0:1], v[0:1], v[180:181], v[10:11] op_sel_hi:[1,0,1]
	ds_read2_b32 v[180:181], v91 offset0:64 offset1:96
	ds_read2_b32 v[184:185], v93 offset0:64 offset1:96
	ds_read2_b32 v[186:187], v69 offset0:64 offset1:96
	ds_read2_b32 v[188:189], v71 offset0:64 offset1:96
	ds_read2_b32 v[190:191], v73 offset0:64 offset1:96
	s_waitcnt vmcnt(3) lgkmcnt(6)
	v_pk_fma_f32 v[10:11], v[16:17], v[8:9], v[18:19] op_sel_hi:[1,0,1]
	v_pk_fma_f32 v[12:13], v[14:15], v[8:9], v[12:13] op_sel_hi:[1,0,1]
	s_waitcnt lgkmcnt(5)
	v_pk_fma_f32 v[176:177], v[14:15], v[182:183], v[176:177] op_sel_hi:[1,0,1]
	s_waitcnt lgkmcnt(4)
; __device__ __forceinline__ void p0_mod_item(const Params& p, LAS unsigned char* lds, int item) {
;     ...
;     for (int pass = 0; pass < 32; ++pass) { const int i = pass * 32 + rs; const f32x4 w = *(const f32x4*)(p.w_ada + (size_t)i * NMOD + j0 + 4 * l16);
; #pragma unroll
;         for (int b = 0; b < 8; ++b) acc[b] += cs[b * DM + i] * w; }
	v_pk_fma_f32 v[104:105], v[14:15], v[180:181], v[104:105] op_sel_hi:[1,0,1]
	s_waitcnt lgkmcnt(3)
	v_pk_fma_f32 v[156:157], v[14:15], v[184:185], v[156:157] op_sel_hi:[1,0,1]
	s_waitcnt lgkmcnt(2)
	v_pk_fma_f32 v[160:161], v[14:15], v[186:187], v[160:161] op_sel_hi:[1,0,1]
	s_waitcnt lgkmcnt(1)
	v_pk_fma_f32 v[178:179], v[14:15], v[188:189], v[178:179] op_sel_hi:[1,0,1]
	s_waitcnt lgkmcnt(0)
	v_pk_fma_f32 v[164:165], v[14:15], v[190:191], v[164:165] op_sel_hi:[1,0,1]
	v_pk_fma_f32 v[0:1], v[14:15], v[192:193], v[0:1] op_sel_hi:[1,0,1]
	v_mov_b32_e32 v8, v9
	v_lshl_add_u64 v[14:15], v[100:101], 0, v[80:81]
	v_pk_fma_f32 v[102:103], v[16:17], v[182:183], v[102:103] op_sel_hi:[1,0,1]
	v_pk_fma_f32 v[166:167], v[16:17], v[180:181], v[166:167] op_sel_hi:[1,0,1]
	v_pk_fma_f32 v[158:159], v[16:17], v[184:185], v[158:159] op_sel_hi:[1,0,1]
	v_pk_fma_f32 v[168:169], v[16:17], v[186:187], v[168:169] op_sel_hi:[1,0,1]
	v_pk_fma_f32 v[174:175], v[16:17], v[188:189], v[174:175] op_sel_hi:[1,0,1]
	v_pk_fma_f32 v[162:163], v[16:17], v[190:191], v[162:163] op_sel_hi:[1,0,1]
	v_pk_fma_f32 v[2:3], v[16:17], v[192:193], v[2:3] op_sel_hi:[1,0,1]
	global_load_dwordx4 v[16:19], v[14:15], off nt
	s_waitcnt vmcnt(3)
	v_pk_fma_f32 v[14:15], v[6:7], v[8:9], v[10:11] op_sel_hi:[1,0,1]
	v_pk_fma_f32 v[12:13], v[4:5], v[8:9], v[12:13] op_sel_hi:[1,0,1]
	v_mov_b32_e32 v8, v183
	v_pk_fma_f32 v[102:103], v[6:7], v[8:9], v[102:103] op_sel_hi:[1,0,1]
	v_pk_fma_f32 v[176:177], v[4:5], v[8:9], v[176:177] op_sel_hi:[1,0,1]
	v_mov_b32_e32 v8, v181
	v_pk_fma_f32 v[166:167], v[6:7], v[8:9], v[166:167] op_sel_hi:[1,0,1]
	v_pk_fma_f32 v[104:105], v[4:5], v[8:9], v[104:105] op_sel_hi:[1,0,1]
	v_mov_b32_e32 v8, v185
	v_pk_fma_f32 v[158:159], v[6:7], v[8:9], v[158:159] op_sel_hi:[1,0,1]
	v_pk_fma_f32 v[156:157], v[4:5], v[8:9], v[156:157] op_sel_hi:[1,0,1]
	v_mov_b32_e32 v8, v187
	v_pk_fma_f32 v[168:169], v[6:7], v[8:9], v[168:169] op_sel_hi:[1,0,1]
	v_pk_fma_f32 v[160:161], v[4:5], v[8:9], v[160:161] op_sel_hi:[1,0,1]
	v_mov_b32_e32 v8, v189
	v_pk_fma_f32 v[174:175], v[6:7], v[8:9], v[174:175] op_sel_hi:[1,0,1]
	v_pk_fma_f32 v[178:179], v[4:5], v[8:9], v[178:179] op_sel_hi:[1,0,1]
	v_mov_b32_e32 v8, v191
	v_pk_fma_f32 v[162:163], v[6:7], v[8:9], v[162:163] op_sel_hi:[1,0,1]
	v_pk_fma_f32 v[164:165], v[4:5], v[8:9], v[164:165] op_sel_hi:[1,0,1]
	v_lshl_add_u64 v[8:9], v[100:101], 0, v[82:83]
	global_load_dwordx4 v[8:11], v[8:9], off nt
	v_mov_b32_e32 v180, v193
	v_pk_fma_f32 v[2:3], v[6:7], v[180:181], v[2:3] op_sel_hi:[1,0,1]
	ds_read2_b32 v[6:7], v87 offset0:128 offset1:160
	ds_read2_b32 v[182:183], v89 offset0:128 offset1:160
	v_pk_fma_f32 v[0:1], v[4:5], v[180:181], v[0:1] op_sel_hi:[1,0,1]
	ds_read2_b32 v[180:181], v91 offset0:128 offset1:160
	ds_read2_b32 v[184:185], v93 offset0:128 offset1:160
	ds_read2_b32 v[186:187], v69 offset0:128 offset1:160
	ds_read2_b32 v[188:189], v71 offset0:128 offset1:160
	ds_read2_b32 v[190:191], v73 offset0:128 offset1:160
	ds_read2_b32 v[192:193], v75 offset0:128 offset1:160
	s_waitcnt vmcnt(3) lgkmcnt(7)
	v_pk_fma_f32 v[4:5], v[26:27], v[6:7], v[14:15] op_sel_hi:[1,0,1]
	v_pk_fma_f32 v[12:13], v[24:25], v[6:7], v[12:13] op_sel_hi:[1,0,1]
	v_mov_b32_e32 v6, v7
	s_waitcnt lgkmcnt(6)
	v_pk_fma_f32 v[102:103], v[26:27], v[182:183], v[102:103] op_sel_hi:[1,0,1]
	v_pk_fma_f32 v[176:177], v[24:25], v[182:183], v[176:177] op_sel_hi:[1,0,1]
	s_waitcnt lgkmcnt(5)
	v_pk_fma_f32 v[104:105], v[24:25], v[180:181], v[104:105] op_sel_hi:[1,0,1]
	s_waitcnt lgkmcnt(4)
	v_pk_fma_f32 v[156:157], v[24:25], v[184:185], v[156:157] op_sel_hi:[1,0,1]
	s_waitcnt lgkmcnt(3)
	v_pk_fma_f32 v[160:161], v[24:25], v[186:187], v[160:161] op_sel_hi:[1,0,1]
	s_waitcnt lgkmcnt(2)
	v_pk_fma_f32 v[178:179], v[24:25], v[188:189], v[178:179] op_sel_hi:[1,0,1]
	s_waitcnt lgkmcnt(1)
	v_pk_fma_f32 v[164:165], v[24:25], v[190:191], v[164:165] op_sel_hi:[1,0,1]
	s_waitcnt lgkmcnt(0)
	v_pk_fma_f32 v[0:1], v[24:25], v[192:193], v[0:1] op_sel_hi:[1,0,1]
	s_waitcnt vmcnt(2)
	v_pk_fma_f32 v[4:5], v[22:23], v[6:7], v[4:5] op_sel_hi:[1,0,1]
	v_pk_fma_f32 v[6:7], v[20:21], v[6:7], v[12:13] op_sel_hi:[1,0,1]
	v_lshl_add_u64 v[12:13], v[100:101], 0, v[84:85]
	v_mov_b32_e32 v24, v183
	v_pk_fma_f32 v[166:167], v[26:27], v[180:181], v[166:167] op_sel_hi:[1,0,1]
	v_pk_fma_f32 v[158:159], v[26:27], v[184:185], v[158:159] op_sel_hi:[1,0,1]
	v_pk_fma_f32 v[168:169], v[26:27], v[186:187], v[168:169] op_sel_hi:[1,0,1]
	v_pk_fma_f32 v[174:175], v[26:27], v[188:189], v[174:175] op_sel_hi:[1,0,1]
	v_pk_fma_f32 v[162:163], v[26:27], v[190:191], v[162:163] op_sel_hi:[1,0,1]
	v_pk_fma_f32 v[2:3], v[26:27], v[192:193], v[2:3] op_sel_hi:[1,0,1]
	global_load_dwordx4 v[12:15], v[12:13], off nt
	v_pk_fma_f32 v[26:27], v[22:23], v[24:25], v[102:103] op_sel_hi:[1,0,1]
	v_mov_b32_e32 v102, v181
	v_pk_fma_f32 v[166:167], v[22:23], v[102:103], v[166:167] op_sel_hi:[1,0,1]
	v_pk_fma_f32 v[102:103], v[20:21], v[102:103], v[104:105] op_sel_hi:[1,0,1]
	v_mov_b32_e32 v104, v185
	v_pk_fma_f32 v[158:159], v[22:23], v[104:105], v[158:159] op_sel_hi:[1,0,1]
	v_pk_fma_f32 v[104:105], v[20:21], v[104:105], v[156:157] op_sel_hi:[1,0,1]
	v_mov_b32_e32 v156, v187
	v_pk_fma_f32 v[24:25], v[20:21], v[24:25], v[176:177] op_sel_hi:[1,0,1]
	v_pk_fma_f32 v[168:169], v[22:23], v[156:157], v[168:169] op_sel_hi:[1,0,1]
	v_pk_fma_f32 v[156:157], v[20:21], v[156:157], v[160:161] op_sel_hi:[1,0,1]
	v_mov_b32_e32 v160, v189
	v_mov_b32_e32 v176, v191
	v_pk_fma_f32 v[174:175], v[22:23], v[160:161], v[174:175] op_sel_hi:[1,0,1]
	v_pk_fma_f32 v[160:161], v[20:21], v[160:161], v[178:179] op_sel_hi:[1,0,1]
	v_pk_fma_f32 v[162:163], v[22:23], v[176:177], v[162:163] op_sel_hi:[1,0,1]
	v_pk_fma_f32 v[164:165], v[20:21], v[176:177], v[164:165] op_sel_hi:[1,0,1]
	ds_read2_b32 v[176:177], v87 offset0:192 offset1:224
	v_mov_b32_e32 v178, v193
	v_mov_b32_e32 v87, v29
	v_pk_fma_f32 v[20:21], v[20:21], v[178:179], v[0:1] op_sel_hi:[1,0,1]
	v_lshl_add_u64 v[0:1], v[100:101], 0, v[86:87]
	ds_read2_b32 v[180:181], v89 offset0:192 offset1:224
	v_pk_fma_f32 v[22:23], v[22:23], v[178:179], v[2:3] op_sel_hi:[1,0,1]
	ds_read2_b32 v[178:179], v91 offset0:192 offset1:224
	ds_read2_b32 v[182:183], v93 offset0:192 offset1:224
	global_load_dwordx4 v[0:3], v[0:1], off nt
	ds_read2_b32 v[184:185], v69 offset0:192 offset1:224
	ds_read2_b32 v[186:187], v71 offset0:192 offset1:224
	ds_read2_b32 v[188:189], v73 offset0:192 offset1:224
	ds_read2_b32 v[190:191], v75 offset0:192 offset1:224
	s_waitcnt vmcnt(3) lgkmcnt(7)
; __device__ __forceinline__ void p0_mod_item(const Params& p, LAS unsigned char* lds, int item) {
;     ...
;     for (int pass = 0; pass < 32; ++pass) { const int i = pass * 32 + rs; const f32x4 w = *(const f32x4*)(p.w_ada + (size_t)i * NMOD + j0 + 4 * l16);
; #pragma unroll
;         for (int b = 0; b < 8; ++b) acc[b] += cs[b * DM + i] * w; }
	v_pk_fma_f32 v[4:5], v[18:19], v[176:177], v[4:5] op_sel_hi:[1,0,1]
	v_pk_fma_f32 v[6:7], v[16:17], v[176:177], v[6:7] op_sel_hi:[1,0,1]
	s_waitcnt lgkmcnt(6)
	v_pk_fma_f32 v[24:25], v[16:17], v[180:181], v[24:25] op_sel_hi:[1,0,1]
	s_waitcnt lgkmcnt(5)
	v_pk_fma_f32 v[102:103], v[16:17], v[178:179], v[102:103] op_sel_hi:[1,0,1]
	s_waitcnt lgkmcnt(4)
	v_pk_fma_f32 v[104:105], v[16:17], v[182:183], v[104:105] op_sel_hi:[1,0,1]
	s_waitcnt lgkmcnt(3)
	v_pk_fma_f32 v[156:157], v[16:17], v[184:185], v[156:157] op_sel_hi:[1,0,1]
	s_waitcnt lgkmcnt(2)
	v_pk_fma_f32 v[160:161], v[16:17], v[186:187], v[160:161] op_sel_hi:[1,0,1]
	s_waitcnt lgkmcnt(1)
	v_pk_fma_f32 v[164:165], v[16:17], v[188:189], v[164:165] op_sel_hi:[1,0,1]
	s_waitcnt lgkmcnt(0)
	v_pk_fma_f32 v[16:17], v[16:17], v[190:191], v[20:21] op_sel_hi:[1,0,1]
	v_mov_b32_e32 v20, v177
	v_pk_fma_f32 v[26:27], v[18:19], v[180:181], v[26:27] op_sel_hi:[1,0,1]
	v_pk_fma_f32 v[166:167], v[18:19], v[178:179], v[166:167] op_sel_hi:[1,0,1]
	v_pk_fma_f32 v[158:159], v[18:19], v[182:183], v[158:159] op_sel_hi:[1,0,1]
	v_pk_fma_f32 v[168:169], v[18:19], v[184:185], v[168:169] op_sel_hi:[1,0,1]
	v_pk_fma_f32 v[174:175], v[18:19], v[186:187], v[174:175] op_sel_hi:[1,0,1]
	v_pk_fma_f32 v[162:163], v[18:19], v[188:189], v[162:163] op_sel_hi:[1,0,1]
	v_pk_fma_f32 v[18:19], v[18:19], v[190:191], v[22:23] op_sel_hi:[1,0,1]
	s_waitcnt vmcnt(2)
	v_pk_fma_f32 v[22:23], v[10:11], v[20:21], v[4:5] op_sel_hi:[1,0,1]
	v_mov_b32_e32 v4, v181
	v_pk_fma_f32 v[176:177], v[8:9], v[20:21], v[6:7] op_sel_hi:[1,0,1]
	v_pk_fma_f32 v[26:27], v[10:11], v[4:5], v[26:27] op_sel_hi:[1,0,1]
	v_pk_fma_f32 v[24:25], v[8:9], v[4:5], v[24:25] op_sel_hi:[1,0,1]
	v_mov_b32_e32 v4, v179
	v_mov_b32_e32 v20, v185
	v_pk_fma_f32 v[166:167], v[10:11], v[4:5], v[166:167] op_sel_hi:[1,0,1]
	v_pk_fma_f32 v[102:103], v[8:9], v[4:5], v[102:103] op_sel_hi:[1,0,1]
	v_mov_b32_e32 v4, v183
	v_mov_b32_e32 v89, v29
	v_pk_fma_f32 v[168:169], v[10:11], v[20:21], v[168:169] op_sel_hi:[1,0,1]
	v_pk_fma_f32 v[156:157], v[8:9], v[20:21], v[156:157] op_sel_hi:[1,0,1]
	v_mov_b32_e32 v20, v187
	v_pk_fma_f32 v[158:159], v[10:11], v[4:5], v[158:159] op_sel_hi:[1,0,1]
	v_pk_fma_f32 v[104:105], v[8:9], v[4:5], v[104:105] op_sel_hi:[1,0,1]
	v_lshl_add_u64 v[4:5], v[100:101], 0, v[88:89]
	v_pk_fma_f32 v[174:175], v[10:11], v[20:21], v[174:175] op_sel_hi:[1,0,1]
	v_pk_fma_f32 v[160:161], v[8:9], v[20:21], v[160:161] op_sel_hi:[1,0,1]
	v_mov_b32_e32 v20, v189
	v_mov_b32_e32 v178, v191
	v_mov_b32_e32 v91, v29
	global_load_dwordx4 v[4:7], v[4:5], off nt
	v_pk_fma_f32 v[164:165], v[8:9], v[20:21], v[164:165] op_sel_hi:[1,0,1]
	v_pk_fma_f32 v[16:17], v[8:9], v[178:179], v[16:17] op_sel_hi:[1,0,1]
	v_lshl_add_u64 v[8:9], v[100:101], 0, v[90:91]
	v_pk_fma_f32 v[162:163], v[10:11], v[20:21], v[162:163] op_sel_hi:[1,0,1]
	v_pk_fma_f32 v[18:19], v[10:11], v[178:179], v[18:19] op_sel_hi:[1,0,1]
	global_load_dwordx4 v[8:11], v[8:9], off nt
	v_add_u32_e32 v21, 0xc00, v126
	ds_read2_b32 v[180:181], v21 offset1:32
	v_add_u32_e32 v20, 0x1c00, v126
	v_add_u32_e32 v75, 0x7c00, v126
	ds_read2_b32 v[182:183], v20 offset1:32
	ds_read2_b32 v[194:195], v75 offset1:32
	s_waitcnt vmcnt(3) lgkmcnt(2)
	v_pk_fma_f32 v[178:179], v[14:15], v[180:181], v[22:23] op_sel_hi:[1,0,1]
	v_add_u32_e32 v23, 0x2c00, v126
	ds_read2_b32 v[184:185], v23 offset1:32
	v_add_u32_e32 v22, 0x3c00, v126
	ds_read2_b32 v[186:187], v22 offset1:32
	v_add_u32_e32 v69, 0x4c00, v126
	ds_read2_b32 v[188:189], v69 offset1:32
	v_add_u32_e32 v71, 0x5c00, v126
	v_add_u32_e32 v73, 0x6c00, v126
	ds_read2_b32 v[190:191], v71 offset1:32
	ds_read2_b32 v[192:193], v73 offset1:32
	s_waitcnt lgkmcnt(6)
	v_pk_fma_f32 v[26:27], v[14:15], v[182:183], v[26:27] op_sel_hi:[1,0,1]
	v_pk_fma_f32 v[24:25], v[12:13], v[182:183], v[24:25] op_sel_hi:[1,0,1]
	s_waitcnt lgkmcnt(5)
	v_pk_fma_f32 v[196:197], v[12:13], v[194:195], v[16:17] op_sel_hi:[1,0,1]
	v_mov_b32_e32 v16, v183
	s_waitcnt lgkmcnt(4)
	v_pk_fma_f32 v[166:167], v[14:15], v[184:185], v[166:167] op_sel_hi:[1,0,1]
	v_pk_fma_f32 v[102:103], v[12:13], v[184:185], v[102:103] op_sel_hi:[1,0,1]
	s_waitcnt lgkmcnt(3)
	v_pk_fma_f32 v[158:159], v[14:15], v[186:187], v[158:159] op_sel_hi:[1,0,1]
	v_pk_fma_f32 v[104:105], v[12:13], v[186:187], v[104:105] op_sel_hi:[1,0,1]
	s_waitcnt lgkmcnt(2)
	v_pk_fma_f32 v[168:169], v[14:15], v[188:189], v[168:169] op_sel_hi:[1,0,1]
	v_pk_fma_f32 v[156:157], v[12:13], v[188:189], v[156:157] op_sel_hi:[1,0,1]
	v_pk_fma_f32 v[176:177], v[12:13], v[180:181], v[176:177] op_sel_hi:[1,0,1]
	s_waitcnt lgkmcnt(1)
	v_pk_fma_f32 v[174:175], v[14:15], v[190:191], v[174:175] op_sel_hi:[1,0,1]
	s_waitcnt vmcnt(2)
	v_pk_fma_f32 v[26:27], v[2:3], v[16:17], v[26:27] op_sel_hi:[1,0,1]
	v_pk_fma_f32 v[24:25], v[0:1], v[16:17], v[24:25] op_sel_hi:[1,0,1]
	v_mov_b32_e32 v16, v185
	v_pk_fma_f32 v[166:167], v[2:3], v[16:17], v[166:167] op_sel_hi:[1,0,1]
	v_pk_fma_f32 v[102:103], v[0:1], v[16:17], v[102:103] op_sel_hi:[1,0,1]
	v_mov_b32_e32 v16, v187
	v_pk_fma_f32 v[158:159], v[2:3], v[16:17], v[158:159] op_sel_hi:[1,0,1]
	v_pk_fma_f32 v[104:105], v[0:1], v[16:17], v[104:105] op_sel_hi:[1,0,1]
	v_mov_b32_e32 v16, v189
	v_pk_fma_f32 v[160:161], v[12:13], v[190:191], v[160:161] op_sel_hi:[1,0,1]
	s_waitcnt lgkmcnt(0)
; __device__ __forceinline__ void p0_mod_item(const Params& p, LAS unsigned char* lds, int item) {
;     ...
;     for (int pass = 0; pass < 32; ++pass) { const int i = pass * 32 + rs; const f32x4 w = *(const f32x4*)(p.w_ada + (size_t)i * NMOD + j0 + 4 * l16);
; #pragma unroll
;         for (int b = 0; b < 8; ++b) acc[b] += cs[b * DM + i] * w; }
	v_pk_fma_f32 v[164:165], v[12:13], v[192:193], v[164:165] op_sel_hi:[1,0,1]
	v_mov_b32_e32 v12, v181
	v_mov_b32_e32 v93, v29
	v_pk_fma_f32 v[168:169], v[2:3], v[16:17], v[168:169] op_sel_hi:[1,0,1]
	v_pk_fma_f32 v[156:157], v[0:1], v[16:17], v[156:157] op_sel_hi:[1,0,1]
	v_mov_b32_e32 v16, v191
	v_pk_fma_f32 v[162:163], v[14:15], v[192:193], v[162:163] op_sel_hi:[1,0,1]
	v_pk_fma_f32 v[18:19], v[14:15], v[194:195], v[18:19] op_sel_hi:[1,0,1]
	v_pk_fma_f32 v[178:179], v[2:3], v[12:13], v[178:179] op_sel_hi:[1,0,1]
	v_pk_fma_f32 v[176:177], v[0:1], v[12:13], v[176:177] op_sel_hi:[1,0,1]
	v_lshl_add_u64 v[12:13], v[100:101], 0, v[92:93]
	v_pk_fma_f32 v[174:175], v[2:3], v[16:17], v[174:175] op_sel_hi:[1,0,1]
	v_pk_fma_f32 v[160:161], v[0:1], v[16:17], v[160:161] op_sel_hi:[1,0,1]
	v_mov_b32_e32 v16, v193
	v_mov_b32_e32 v180, v195
	global_load_dwordx4 v[12:15], v[12:13], off nt
	v_pk_fma_f32 v[162:163], v[2:3], v[16:17], v[162:163] op_sel_hi:[1,0,1]
	v_pk_fma_f32 v[182:183], v[2:3], v[180:181], v[18:19] op_sel_hi:[1,0,1]
	v_lshl_add_u64 v[2:3], v[100:101], 0, v[94:95]
	v_pk_fma_f32 v[164:165], v[0:1], v[16:17], v[164:165] op_sel_hi:[1,0,1]
	global_load_dwordx4 v[16:19], v[2:3], off nt
	ds_read2_b32 v[184:185], v21 offset0:64 offset1:96
	ds_read2_b32 v[186:187], v20 offset0:64 offset1:96
	v_pk_fma_f32 v[180:181], v[0:1], v[180:181], v[196:197] op_sel_hi:[1,0,1]
	ds_read2_b32 v[188:189], v23 offset0:64 offset1:96
	ds_read2_b32 v[190:191], v22 offset0:64 offset1:96
	ds_read2_b32 v[192:193], v69 offset0:64 offset1:96
	ds_read2_b32 v[194:195], v71 offset0:64 offset1:96
	ds_read2_b32 v[196:197], v73 offset0:64 offset1:96
	ds_read2_b32 v[198:199], v75 offset0:64 offset1:96
	v_lshl_add_u64 v[0:1], v[100:101], 0, v[96:97]
	global_load_dwordx4 v[0:3], v[0:1], off nt
	s_waitcnt vmcnt(4) lgkmcnt(7)
	v_pk_fma_f32 v[178:179], v[6:7], v[184:185], v[178:179] op_sel_hi:[1,0,1]
	v_pk_fma_f32 v[176:177], v[4:5], v[184:185], v[176:177] op_sel_hi:[1,0,1]
	s_waitcnt lgkmcnt(6)
	v_pk_fma_f32 v[24:25], v[4:5], v[186:187], v[24:25] op_sel_hi:[1,0,1]
	s_waitcnt lgkmcnt(5)
	v_pk_fma_f32 v[102:103], v[4:5], v[188:189], v[102:103] op_sel_hi:[1,0,1]
	s_waitcnt lgkmcnt(4)
	v_pk_fma_f32 v[104:105], v[4:5], v[190:191], v[104:105] op_sel_hi:[1,0,1]
	s_waitcnt lgkmcnt(3)
	v_pk_fma_f32 v[156:157], v[4:5], v[192:193], v[156:157] op_sel_hi:[1,0,1]
	s_waitcnt lgkmcnt(2)
	v_pk_fma_f32 v[160:161], v[4:5], v[194:195], v[160:161] op_sel_hi:[1,0,1]
	s_waitcnt lgkmcnt(1)
	v_pk_fma_f32 v[164:165], v[4:5], v[196:197], v[164:165] op_sel_hi:[1,0,1]
	s_waitcnt lgkmcnt(0)
	v_pk_fma_f32 v[180:181], v[4:5], v[198:199], v[180:181] op_sel_hi:[1,0,1]
	v_mov_b32_e32 v4, v185
	v_pk_fma_f32 v[26:27], v[6:7], v[186:187], v[26:27] op_sel_hi:[1,0,1]
	s_waitcnt vmcnt(3)
	v_pk_fma_f32 v[178:179], v[10:11], v[4:5], v[178:179] op_sel_hi:[1,0,1]
	v_pk_fma_f32 v[176:177], v[8:9], v[4:5], v[176:177] op_sel_hi:[1,0,1]
	v_mov_b32_e32 v4, v187
	v_pk_fma_f32 v[166:167], v[6:7], v[188:189], v[166:167] op_sel_hi:[1,0,1]
	v_pk_fma_f32 v[26:27], v[10:11], v[4:5], v[26:27] op_sel_hi:[1,0,1]
	v_pk_fma_f32 v[24:25], v[8:9], v[4:5], v[24:25] op_sel_hi:[1,0,1]
	v_mov_b32_e32 v4, v189
	v_pk_fma_f32 v[158:159], v[6:7], v[190:191], v[158:159] op_sel_hi:[1,0,1]
	v_pk_fma_f32 v[166:167], v[10:11], v[4:5], v[166:167] op_sel_hi:[1,0,1]
	v_pk_fma_f32 v[102:103], v[8:9], v[4:5], v[102:103] op_sel_hi:[1,0,1]
	v_mov_b32_e32 v4, v191
	v_pk_fma_f32 v[168:169], v[6:7], v[192:193], v[168:169] op_sel_hi:[1,0,1]
	v_pk_fma_f32 v[158:159], v[10:11], v[4:5], v[158:159] op_sel_hi:[1,0,1]
	v_pk_fma_f32 v[104:105], v[8:9], v[4:5], v[104:105] op_sel_hi:[1,0,1]
	v_mov_b32_e32 v4, v193
	v_pk_fma_f32 v[174:175], v[6:7], v[194:195], v[174:175] op_sel_hi:[1,0,1]
	v_pk_fma_f32 v[168:169], v[10:11], v[4:5], v[168:169] op_sel_hi:[1,0,1]
	v_pk_fma_f32 v[156:157], v[8:9], v[4:5], v[156:157] op_sel_hi:[1,0,1]
	v_mov_b32_e32 v4, v195
	v_pk_fma_f32 v[174:175], v[10:11], v[4:5], v[174:175] op_sel_hi:[1,0,1]
	v_pk_fma_f32 v[160:161], v[8:9], v[4:5], v[160:161] op_sel_hi:[1,0,1]
	v_lshl_add_u64 v[4:5], v[100:101], 0, v[98:99]
	v_pk_fma_f32 v[162:163], v[6:7], v[196:197], v[162:163] op_sel_hi:[1,0,1]
	v_pk_fma_f32 v[182:183], v[6:7], v[198:199], v[182:183] op_sel_hi:[1,0,1]
	global_load_dwordx4 v[4:7], v[4:5], off nt
	v_mov_b32_e32 v100, v197
	v_mov_b32_e32 v184, v199
	v_pk_fma_f32 v[162:163], v[10:11], v[100:101], v[162:163] op_sel_hi:[1,0,1]
	v_pk_fma_f32 v[100:101], v[8:9], v[100:101], v[164:165] op_sel_hi:[1,0,1]
	ds_read2_b32 v[164:165], v21 offset0:128 offset1:160
	v_pk_fma_f32 v[10:11], v[10:11], v[184:185], v[182:183] op_sel_hi:[1,0,1]
	ds_read2_b32 v[182:183], v20 offset0:128 offset1:160
	v_pk_fma_f32 v[8:9], v[8:9], v[184:185], v[180:181] op_sel_hi:[1,0,1]
	ds_read2_b32 v[180:181], v23 offset0:128 offset1:160
	ds_read2_b32 v[184:185], v22 offset0:128 offset1:160
	ds_read2_b32 v[186:187], v69 offset0:128 offset1:160
	ds_read2_b32 v[188:189], v71 offset0:128 offset1:160
	ds_read2_b32 v[190:191], v73 offset0:128 offset1:160
	ds_read2_b32 v[192:193], v75 offset0:128 offset1:160
	s_waitcnt vmcnt(3) lgkmcnt(7)
	v_pk_fma_f32 v[178:179], v[14:15], v[164:165], v[178:179] op_sel_hi:[1,0,1]
	v_pk_fma_f32 v[176:177], v[12:13], v[164:165], v[176:177] op_sel_hi:[1,0,1]
	s_waitcnt lgkmcnt(6)
	v_pk_fma_f32 v[26:27], v[14:15], v[182:183], v[26:27] op_sel_hi:[1,0,1]
	v_pk_fma_f32 v[24:25], v[12:13], v[182:183], v[24:25] op_sel_hi:[1,0,1]
	v_mov_b32_e32 v164, v183
	s_waitcnt lgkmcnt(5)
	v_pk_fma_f32 v[166:167], v[14:15], v[180:181], v[166:167] op_sel_hi:[1,0,1]
	v_pk_fma_f32 v[102:103], v[12:13], v[180:181], v[102:103] op_sel_hi:[1,0,1]
	s_waitcnt vmcnt(2)
; #define LAS __attribute__((address_space(3)))
; __device__ __forceinline__ void p0_mod_item(const Params& p, LAS unsigned char* lds, int item) {
;     ...
;     for (int pass = 0; pass < 32; ++pass) { const int i = pass * 32 + rs; const f32x4 w = *(const f32x4*)(p.w_ada + (size_t)i * NMOD + j0 + 4 * l16);
; #pragma unroll
;         for (int b = 0; b < 8; ++b) acc[b] += cs[b * DM + i] * w; }
; #pragma unroll
;     for (int b = 0; b < 8; ++b) *(LAS f32x4*)(red + (rs * 8 + b) * 64 + 4 * l16) = acc[b];
;     __syncthreads();
;     { const int b = tid >> 6, col = tid & 63; float s = p.b_ada[j0 + col];
	v_pk_fma_f32 v[26:27], v[18:19], v[164:165], v[26:27] op_sel_hi:[1,0,1]
	v_pk_fma_f32 v[24:25], v[16:17], v[164:165], v[24:25] op_sel_hi:[1,0,1]
	v_mov_b32_e32 v164, v181
	s_waitcnt lgkmcnt(4)
	v_pk_fma_f32 v[158:159], v[14:15], v[184:185], v[158:159] op_sel_hi:[1,0,1]
	v_pk_fma_f32 v[104:105], v[12:13], v[184:185], v[104:105] op_sel_hi:[1,0,1]
	v_pk_fma_f32 v[166:167], v[18:19], v[164:165], v[166:167] op_sel_hi:[1,0,1]
	v_pk_fma_f32 v[102:103], v[16:17], v[164:165], v[102:103] op_sel_hi:[1,0,1]
	v_mov_b32_e32 v164, v185
	s_waitcnt lgkmcnt(3)
	v_pk_fma_f32 v[168:169], v[14:15], v[186:187], v[168:169] op_sel_hi:[1,0,1]
	v_pk_fma_f32 v[156:157], v[12:13], v[186:187], v[156:157] op_sel_hi:[1,0,1]
	v_pk_fma_f32 v[158:159], v[18:19], v[164:165], v[158:159] op_sel_hi:[1,0,1]
	v_pk_fma_f32 v[104:105], v[16:17], v[164:165], v[104:105] op_sel_hi:[1,0,1]
	v_mov_b32_e32 v164, v187
	s_waitcnt lgkmcnt(2)
	v_pk_fma_f32 v[174:175], v[14:15], v[188:189], v[174:175] op_sel_hi:[1,0,1]
	v_pk_fma_f32 v[160:161], v[12:13], v[188:189], v[160:161] op_sel_hi:[1,0,1]
	s_waitcnt lgkmcnt(1)
	v_pk_fma_f32 v[100:101], v[12:13], v[190:191], v[100:101] op_sel_hi:[1,0,1]
	s_waitcnt lgkmcnt(0)
	v_pk_fma_f32 v[8:9], v[12:13], v[192:193], v[8:9] op_sel_hi:[1,0,1]
	v_mov_b32_e32 v12, v165
	v_pk_fma_f32 v[168:169], v[18:19], v[164:165], v[168:169] op_sel_hi:[1,0,1]
	v_pk_fma_f32 v[156:157], v[16:17], v[164:165], v[156:157] op_sel_hi:[1,0,1]
	v_mov_b32_e32 v164, v189
	v_pk_fma_f32 v[162:163], v[14:15], v[190:191], v[162:163] op_sel_hi:[1,0,1]
	v_pk_fma_f32 v[10:11], v[14:15], v[192:193], v[10:11] op_sel_hi:[1,0,1]
	v_pk_fma_f32 v[14:15], v[18:19], v[12:13], v[178:179] op_sel_hi:[1,0,1]
	v_pk_fma_f32 v[12:13], v[16:17], v[12:13], v[176:177] op_sel_hi:[1,0,1]
	v_pk_fma_f32 v[174:175], v[18:19], v[164:165], v[174:175] op_sel_hi:[1,0,1]
	v_pk_fma_f32 v[160:161], v[16:17], v[164:165], v[160:161] op_sel_hi:[1,0,1]
	v_mov_b32_e32 v164, v191
	v_mov_b32_e32 v176, v193
	v_pk_fma_f32 v[162:163], v[18:19], v[164:165], v[162:163] op_sel_hi:[1,0,1]
	v_pk_fma_f32 v[100:101], v[16:17], v[164:165], v[100:101] op_sel_hi:[1,0,1]
	v_pk_fma_f32 v[10:11], v[18:19], v[176:177], v[10:11] op_sel_hi:[1,0,1]
	ds_read2_b32 v[18:19], v20 offset0:192 offset1:224
	v_pk_fma_f32 v[8:9], v[16:17], v[176:177], v[8:9] op_sel_hi:[1,0,1]
	ds_read2_b32 v[16:17], v23 offset0:192 offset1:224
	ds_read2_b32 v[164:165], v21 offset0:192 offset1:224
	ds_read2_b32 v[22:23], v22 offset0:192 offset1:224
	s_waitcnt vmcnt(1) lgkmcnt(3)
	v_pk_fma_f32 v[20:21], v[2:3], v[18:19], v[26:27] op_sel_hi:[1,0,1]
	ds_read2_b32 v[176:177], v71 offset0:192 offset1:224
	s_waitcnt lgkmcnt(3)
	v_pk_fma_f32 v[26:27], v[2:3], v[16:17], v[166:167] op_sel_hi:[1,0,1]
	ds_read2_b32 v[166:167], v69 offset0:192 offset1:224
	ds_read2_b32 v[178:179], v73 offset0:192 offset1:224
	ds_read2_b32 v[180:181], v75 offset0:192 offset1:224
	s_waitcnt lgkmcnt(5)
	v_pk_fma_f32 v[14:15], v[2:3], v[164:165], v[14:15] op_sel_hi:[1,0,1]
	v_pk_fma_f32 v[12:13], v[0:1], v[164:165], v[12:13] op_sel_hi:[1,0,1]
	v_pk_fma_f32 v[24:25], v[0:1], v[18:19], v[24:25] op_sel_hi:[1,0,1]
	v_pk_fma_f32 v[102:103], v[0:1], v[16:17], v[102:103] op_sel_hi:[1,0,1]
	s_waitcnt lgkmcnt(4)
	v_pk_fma_f32 v[158:159], v[2:3], v[22:23], v[158:159] op_sel_hi:[1,0,1]
	v_pk_fma_f32 v[104:105], v[0:1], v[22:23], v[104:105] op_sel_hi:[1,0,1]
	s_waitcnt lgkmcnt(2)
	v_pk_fma_f32 v[156:157], v[0:1], v[166:167], v[156:157] op_sel_hi:[1,0,1]
	v_pk_fma_f32 v[160:161], v[0:1], v[176:177], v[160:161] op_sel_hi:[1,0,1]
	s_waitcnt lgkmcnt(1)
	v_pk_fma_f32 v[100:101], v[0:1], v[178:179], v[100:101] op_sel_hi:[1,0,1]
	s_waitcnt lgkmcnt(0)
	v_pk_fma_f32 v[184:185], v[0:1], v[180:181], v[8:9] op_sel_hi:[1,0,1]
	v_mov_b32_e32 v0, v165
	v_mov_b32_e32 v16, v23
	v_pk_fma_f32 v[168:169], v[2:3], v[166:167], v[168:169] op_sel_hi:[1,0,1]
	v_pk_fma_f32 v[174:175], v[2:3], v[176:177], v[174:175] op_sel_hi:[1,0,1]
	v_pk_fma_f32 v[162:163], v[2:3], v[178:179], v[162:163] op_sel_hi:[1,0,1]
	v_pk_fma_f32 v[182:183], v[2:3], v[180:181], v[10:11] op_sel_hi:[1,0,1]
	s_waitcnt vmcnt(0)
	v_pk_fma_f32 v[2:3], v[6:7], v[0:1], v[14:15] op_sel_hi:[1,0,1]
	v_pk_fma_f32 v[0:1], v[4:5], v[0:1], v[12:13] op_sel_hi:[1,0,1]
	v_mov_b32_e32 v8, v19
	v_mov_b32_e32 v12, v17
	v_pk_fma_f32 v[18:19], v[6:7], v[16:17], v[158:159] op_sel_hi:[1,0,1]
	v_pk_fma_f32 v[16:17], v[4:5], v[16:17], v[104:105] op_sel_hi:[1,0,1]
	v_mov_b32_e32 v104, v179
	v_pk_fma_f32 v[10:11], v[6:7], v[8:9], v[20:21] op_sel_hi:[1,0,1]
	v_pk_fma_f32 v[8:9], v[4:5], v[8:9], v[24:25] op_sel_hi:[1,0,1]
	v_pk_fma_f32 v[14:15], v[6:7], v[12:13], v[26:27] op_sel_hi:[1,0,1]
	v_pk_fma_f32 v[12:13], v[4:5], v[12:13], v[102:103] op_sel_hi:[1,0,1]
	v_mov_b32_e32 v20, v167
	v_mov_b32_e32 v24, v177
	v_pk_fma_f32 v[102:103], v[6:7], v[104:105], v[162:163] op_sel_hi:[1,0,1]
	v_pk_fma_f32 v[100:101], v[4:5], v[104:105], v[100:101] op_sel_hi:[1,0,1]
	v_mov_b32_e32 v104, v181
	v_add_u32_e32 v69, v121, v122
	v_pk_fma_f32 v[22:23], v[6:7], v[20:21], v[168:169] op_sel_hi:[1,0,1]
	v_pk_fma_f32 v[20:21], v[4:5], v[20:21], v[156:157] op_sel_hi:[1,0,1]
	v_pk_fma_f32 v[26:27], v[6:7], v[24:25], v[174:175] op_sel_hi:[1,0,1]
	v_pk_fma_f32 v[24:25], v[4:5], v[24:25], v[160:161] op_sel_hi:[1,0,1]
	v_pk_fma_f32 v[6:7], v[6:7], v[104:105], v[182:183] op_sel_hi:[1,0,1]
	v_pk_fma_f32 v[4:5], v[4:5], v[104:105], v[184:185] op_sel_hi:[1,0,1]
	ds_write_b128 v69, v[0:3] offset:32768
	ds_write_b128 v69, v[8:11] offset:33024
	ds_write_b128 v69, v[12:15] offset:33280
	ds_write_b128 v69, v[16:19] offset:33536
	ds_write_b128 v69, v[20:23] offset:33792
	ds_write_b128 v69, v[24:27] offset:34048
	ds_write_b128 v69, v[100:103] offset:34304
	ds_write_b128 v69, v[4:7] offset:34560
	v_or_b32_e32 v0, s14, v37
	v_ashrrev_i32_e32 v1, 31, v0
	v_lshl_add_u64 v[0:1], v[0:1], 2, s[42:43]
	s_waitcnt lgkmcnt(0)
	s_barrier
	global_load_dword v0, v[0:1], off
